# scan staging: weight-item loads issued as global loads so the chunk barrier's LDS wait does not wait on them; v fetched 8 steps at a time
# speedup vs baseline: 1.0029x; 1.0013x over previous
.Lscan_ph1_sel:
	v_mov_b32_e32 v0, s0
	v_mov_b32_e32 v33, s28
	v_mov_b64_e32 v[2:3], s[4:5]
	v_lshrrev_b32_e32 v4, 5, v33
	v_cvt_f32_u32_e32 v6, v4
	v_cvt_f32_u32_sdwa v5, v0 dst_sel:DWORD dst_unused:UNUSED_PAD src0_sel:WORD_0
	v_mov_b32_e32 v105, v1
	v_rcp_iflag_f32_e32 v7, v6
	s_nop 0
	v_mul_f32_e32 v7, v5, v7
	v_trunc_f32_e32 v7, v7
	v_fma_f32 v5, -v7, v6, v5
	v_cvt_u32_f32_e32 v7, v7
	v_cmp_ge_f32_e64 vcc, |v5|, v6
	s_nop 1
	v_addc_co_u32_e32 v5, vcc, 0, v7, vcc
	v_and_b32_e32 v6, 0xffff, v5
	v_mul_lo_u16_e32 v4, v5, v4
	v_sub_u16_e32 v0, v0, v4
	v_lshl_or_b32 v4, v6, 6, v147
	v_mul_hi_u32_u24_e32 v5, v4, v33
	v_mul_u32_u24_e32 v4, v4, v33
	v_lshlrev_b16_e32 v0, 5, v0
	v_lshl_add_u64 v[2:3], v[4:5], 2, v[2:3]
	v_lshlrev_b32_e32 v0, 2, v0
	v_lshl_add_u64 v[2:3], v[2:3], 0, v[0:1]
	v_lshl_add_u64 v[58:59], v[2:3], 0, v[104:105]
	v_lshlrev_b32_e32 v0, 1, v33
	v_lshl_add_u64 v[4:5], v[0:1], 2, v[58:59]
	v_lshlrev_b32_e32 v0, 2, v33
	global_load_dword v2, v[58:59], off nt
	global_load_dword v3, v[4:5], off nt
	v_lshl_add_u64 v[4:5], v[0:1], 2, v[58:59]
	v_mul_u32_u24_e32 v0, 6, v33
	v_lshlrev_b32_e32 v0, 2, v0
	v_lshl_add_u64 v[6:7], v[58:59], 0, v[0:1]
	v_lshlrev_b32_e32 v0, 3, v33
	global_load_dword v4, v[4:5], off nt
	s_nop 0
	global_load_dword v5, v[6:7], off nt
	v_lshl_add_u64 v[6:7], v[0:1], 2, v[58:59]
	v_mul_u32_u24_e32 v0, 10, v33
	v_lshlrev_b32_e32 v0, 2, v0
	v_lshl_add_u64 v[8:9], v[58:59], 0, v[0:1]
	v_mul_u32_u24_e32 v0, 12, v33
	v_lshlrev_b32_e32 v0, 2, v0
	global_load_dword v6, v[6:7], off nt
	s_nop 0
	global_load_dword v7, v[8:9], off nt
	v_lshl_add_u64 v[8:9], v[58:59], 0, v[0:1]
	v_mul_u32_u24_e32 v0, 14, v33
	v_lshlrev_b32_e32 v0, 2, v0
	v_lshl_add_u64 v[10:11], v[58:59], 0, v[0:1]
	v_lshlrev_b32_e32 v0, 4, v33
	global_load_dword v8, v[8:9], off nt
	s_nop 0
	global_load_dword v9, v[10:11], off nt
	v_lshl_add_u64 v[10:11], v[0:1], 2, v[58:59]
	v_mul_u32_u24_e32 v0, 18, v33
	v_lshlrev_b32_e32 v0, 2, v0
	v_lshl_add_u64 v[12:13], v[58:59], 0, v[0:1]
	v_mul_u32_u24_e32 v0, 20, v33
	v_lshlrev_b32_e32 v0, 2, v0
	global_load_dword v10, v[10:11], off nt
	s_nop 0
	global_load_dword v11, v[12:13], off nt
	v_lshl_add_u64 v[12:13], v[58:59], 0, v[0:1]
	v_mul_u32_u24_e32 v0, 22, v33
	v_lshlrev_b32_e32 v0, 2, v0
	v_lshl_add_u64 v[14:15], v[58:59], 0, v[0:1]
	v_mul_u32_u24_e32 v0, 24, v33
	v_lshlrev_b32_e32 v0, 2, v0
	global_load_dword v12, v[12:13], off nt
	s_nop 0
	global_load_dword v13, v[14:15], off nt
	v_lshl_add_u64 v[14:15], v[58:59], 0, v[0:1]
	v_mul_u32_u24_e32 v0, 26, v33
	v_lshlrev_b32_e32 v0, 2, v0
	v_lshl_add_u64 v[16:17], v[58:59], 0, v[0:1]
	v_mul_u32_u24_e32 v0, 28, v33
	v_lshlrev_b32_e32 v0, 2, v0
	global_load_dword v14, v[14:15], off nt
	s_nop 0
	global_load_dword v15, v[16:17], off nt
	v_lshl_add_u64 v[16:17], v[58:59], 0, v[0:1]
	v_mul_u32_u24_e32 v0, 30, v33
	v_lshlrev_b32_e32 v0, 2, v0
	v_lshl_add_u64 v[18:19], v[58:59], 0, v[0:1]
	v_lshlrev_b32_e32 v0, 5, v33
	global_load_dword v16, v[16:17], off nt
	s_nop 0
	global_load_dword v17, v[18:19], off nt
	v_lshl_add_u64 v[18:19], v[0:1], 2, v[58:59]
	v_mul_u32_u24_e32 v0, 34, v33
	v_lshlrev_b32_e32 v0, 2, v0
	v_lshl_add_u64 v[20:21], v[58:59], 0, v[0:1]
	v_mul_u32_u24_e32 v0, 36, v33
	v_lshlrev_b32_e32 v0, 2, v0
	global_load_dword v18, v[18:19], off nt
	s_nop 0
	global_load_dword v19, v[20:21], off nt
	v_lshl_add_u64 v[20:21], v[58:59], 0, v[0:1]
	v_mul_u32_u24_e32 v0, 38, v33
	v_lshlrev_b32_e32 v0, 2, v0
	v_lshl_add_u64 v[22:23], v[58:59], 0, v[0:1]
	v_mul_u32_u24_e32 v0, 40, v33
	v_lshlrev_b32_e32 v0, 2, v0
	global_load_dword v20, v[20:21], off nt
	s_nop 0
	global_load_dword v21, v[22:23], off nt
	v_lshl_add_u64 v[22:23], v[58:59], 0, v[0:1]
	v_mul_u32_u24_e32 v0, 42, v33
	v_lshlrev_b32_e32 v0, 2, v0
	v_lshl_add_u64 v[24:25], v[58:59], 0, v[0:1]
	v_mul_u32_u24_e32 v0, 44, v33
	v_lshlrev_b32_e32 v0, 2, v0
	global_load_dword v22, v[22:23], off nt
	s_nop 0
	global_load_dword v23, v[24:25], off nt
	v_lshl_add_u64 v[24:25], v[58:59], 0, v[0:1]
	v_mul_u32_u24_e32 v0, 46, v33
	v_lshlrev_b32_e32 v0, 2, v0
	v_lshl_add_u64 v[26:27], v[58:59], 0, v[0:1]
	v_mul_u32_u24_e32 v0, 48, v33
	v_lshlrev_b32_e32 v0, 2, v0
	global_load_dword v24, v[24:25], off nt
	s_nop 0
	global_load_dword v25, v[26:27], off nt
	v_lshl_add_u64 v[26:27], v[58:59], 0, v[0:1]
	v_mul_u32_u24_e32 v0, 50, v33
	v_lshlrev_b32_e32 v0, 2, v0
	v_lshl_add_u64 v[28:29], v[58:59], 0, v[0:1]
	v_mul_u32_u24_e32 v0, 52, v33
	v_lshlrev_b32_e32 v0, 2, v0
	global_load_dword v26, v[26:27], off nt
	s_nop 0
	global_load_dword v27, v[28:29], off nt
	v_lshl_add_u64 v[28:29], v[58:59], 0, v[0:1]
	v_mul_u32_u24_e32 v0, 54, v33
	v_lshlrev_b32_e32 v0, 2, v0
	v_lshl_add_u64 v[30:31], v[58:59], 0, v[0:1]
	v_mul_u32_u24_e32 v0, 56, v33
	v_lshlrev_b32_e32 v0, 2, v0
	global_load_dword v28, v[28:29], off nt
	s_nop 0
	global_load_dword v29, v[30:31], off nt
	v_lshl_add_u64 v[30:31], v[58:59], 0, v[0:1]
	v_mul_u32_u24_e32 v0, 58, v33
	v_lshlrev_b32_e32 v0, 2, v0
	v_lshl_add_u64 v[60:61], v[58:59], 0, v[0:1]
	v_mul_u32_u24_e32 v0, 60, v33
	v_lshlrev_b32_e32 v0, 2, v0
	global_load_dword v30, v[30:31], off nt
	s_nop 0
	global_load_dword v31, v[60:61], off nt
	v_lshl_add_u64 v[60:61], v[58:59], 0, v[0:1]
	v_mul_u32_u24_e32 v0, 62, v33
	v_lshlrev_b32_e32 v0, 2, v0
	v_lshl_add_u64 v[58:59], v[58:59], 0, v[0:1]
	global_load_dword v32, v[60:61], off nt
	global_load_dword v33, v[58:59], off nt
